# next-tile index: the division by the tile-group height (always 8 for these shapes) done with shift and mask instead of the float-reciprocal sequence
# speedup vs baseline: 1.0543x; 1.0036x over previous
.LBB0_515:
	s_add_i32 s36, s36, 1
	s_mul_i32 s8, s36, s46
	s_mul_hi_u32 s9, s36, s77
	s_add_i32 s9, s9, s8
	s_mul_i32 s8, s36, s77
	s_mov_b64 s[84:85], s[12:13]
	s_add_u32 s12, s8, s34
	s_addc_u32 s13, s9, s73
	v_mov_b64_e32 v[0:1], s[42:43]
	v_cmp_ge_i64_e64 s[8:9], s[12:13], v[0:1]
	s_mov_b64 s[78:79], s[48:49]
	s_mov_b32 s20, s69
	s_mov_b32 s25, s80
	v_cmp_lt_i64_e64 s[10:11], s[12:13], v[0:1]
	s_and_b64 vcc, exec, s[8:9]
	s_cbranch_vccnz .LBB0_517
	s_ashr_i32 s13, s12, 31
	s_lshr_b32 s13, s13, 29
	s_add_i32 s13, s12, s13
	s_ashr_i32 s48, s13, 3
	s_and_b32 s13, s13, -8
	s_sub_i32 s12, s12, s13
	s_lshr_b32 s13, s12, 31
	s_add_i32 s13, s97, s13
	s_mul_i32 s12, s13, s12
	s_add_i32 s12, s12, s48
	s_abs_i32 s48, s12
	s_mul_hi_u32 s49, s48, s24
	s_mul_i32 s69, s49, s64
	s_ashr_i32 s13, s12, 31
	s_sub_i32 s48, s48, s69
	s_xor_b32 s13, s13, s2
	s_add_i32 s69, s49, 1
	s_sub_i32 s72, s48, s64
	s_cmp_ge_u32 s48, s64
	s_cselect_b32 s49, s69, s49
	s_cselect_b32 s48, s72, s48
	s_add_i32 s69, s49, 1
	s_cmp_ge_u32 s48, s64
	s_cselect_b32 s48, s69, s49
	s_xor_b32 s48, s48, s13
	s_sub_i32 s13, s48, s13
	s_lshl_b32 s48, s13, 3
	s_sub_i32 s49, s86, s48
	s_min_i32 s49, s49, 8
	s_mul_i32 s13, s13, s37
	s_sub_i32 s12, s12, s13
	s_lshr_b32 s80, s12, 3
	s_and_b32 s12, s12, 7
	s_add_i32 s69, s12, s48
